# v22 variant: decode-first workgroups take 19 decode tasks, the other non-scan ones 22
# speedup vs baseline: 1.0230x; 1.0230x over previous
.LBB0_1181:
.LBB0_1182:
	s_cmp_lt_i32 s52, 1
	s_cbranch_scc1 .LBB0_1187
	s_cmp_eq_u32 s52, 1
	s_cbranch_scc1 .LBB0_1185
	s_cmp_eq_u32 s52, 2
	s_cselect_b32 s52, 23, 45
	s_cbranch_execz .LBB0_1186
	s_branch .LBB0_1187

.LBB0_1188:
	s_and_b32 s6, s82, 3
	s_cmp_eq_u32 s6, 3
	s_cselect_b32 s7, 19, 22
	s_cmp_eq_u32 s6, 0
	s_cselect_b32 s6, 1, s7
	s_and_b64 s[4:5], s[4:5], exec
	s_cselect_b32 s44, s6, s25
	s_add_i32 s4, s83, -6
	s_cmp_lt_u32 s4, 2
	s_cselect_b64 s[4:5], -1, 0
	s_or_b64 s[20:21], s[4:5], s[0:1]
	s_add_u32 s45, s26, 0x29800000
	s_addc_u32 s46, s27, 0
	s_add_u32 s18, s26, 0x13200000
	v_readlane_b32 s0, v255, 23
	s_addc_u32 s19, s27, 0
	v_readlane_b32 s14, v255, 37
	v_readlane_b32 s15, v255, 38
	s_add_u32 s30, s14, 0x8200000
	s_addc_u32 s31, s15, 0
	s_add_u32 s47, s14, 0x8300000
	s_addc_u32 s48, s15, 0
	s_add_u32 s49, s26, 0x33a00000
	s_addc_u32 s50, s27, 0
	s_add_u32 s51, s26, 0x34b00000
	s_addc_u32 s52, s27, 0
	s_waitcnt vmcnt(38)
	v_and_b32_e32 v4, 31, v1
	v_readlane_b32 s8, v255, 31
	s_add_u32 s34, s14, 0x8500000
	v_lshlrev_b32_e32 v2, 1, v4
	v_mov_b32_e32 v3, 0
	s_waitcnt vmcnt(5)
	v_ashrrev_i32_e32 v134, 5, v1
	v_readlane_b32 s1, v255, 24
	s_addc_u32 s35, s15, 0
	s_add_i32 s8, 0, 0x24194
	s_mov_b32 s23, 0
	v_cmp_eq_u32_e64 s[72:73], 0, v1
	v_cmp_eq_u32_e64 s[74:75], 0, v4
	v_lshlrev_b32_e32 v120, 3, v4
	v_mov_b32_e32 v121, v3
	v_add_u32_e32 v135, 2, v134
	s_mov_b64 s[0:1], -1
	v_mov_b32_e32 v136, s8
	s_add_i32 s53, 0, 0x241a4
	s_add_i32 s54, 0, 0x241b4
	v_lshlrev_b32_e32 v122, 2, v2
	s_movk_i32 s55, 0x1000
	s_mov_b64 s[36:37], 0x400
	s_add_i32 s64, 0, 0x241a0
	s_movk_i32 s65, 0xc00
	s_mov_b64 s[38:39], 0x1000
	s_mov_b64 s[40:41], -1
	v_readlane_b32 s2, v255, 25
	v_readlane_b32 s3, v255, 26
	v_readlane_b32 s4, v255, 27
	v_readlane_b32 s5, v255, 28
	v_readlane_b32 s6, v255, 29
	v_readlane_b32 s7, v255, 30
	v_readlane_b32 s9, v255, 32
	v_readlane_b32 s10, v255, 33
	v_readlane_b32 s11, v255, 34
	v_readlane_b32 s12, v255, 35
	v_readlane_b32 s13, v255, 36
	s_branch .LBB0_1193
